# previous best + rw_scan loop-edge edit: back edge is one taken conditional branch, the two per-iteration pointer wrap-arounds are selects instead of branches
# speedup vs baseline: 1.0069x; 1.0069x over previous
.LBB0_774:
	s_and_b32 s11, s10, 1
	s_mul_i32 s0, s11, 0x5400
	s_add_i32 s0, s0, 16
	v_lshl_add_u32 v126, v87, 2, s0
	v_add3_u32 v124, s0, v91, v92
	s_lshl_b32 s0, s11, 10
	s_add_i32 s0, s0, 0xe810
	v_add_u32_e32 v127, v91, v92
	v_lshl_add_u32 v127, v127, 4, s0
	ds_read_b128 v[136:139], v127 offset:0
	ds_read_b128 v[184:187], v126 offset:0
	ds_read_b128 v[196:199], v126 offset:768
	ds_read_b128 v[188:191], v126 offset:256
	ds_read_b128 v[200:203], v126 offset:1024
	ds_read_b128 v[192:195], v126 offset:512
	ds_read_b128 v[206:209], v126 offset:1344
	ds_read_b128 v[218:221], v126 offset:2112
	ds_read_b128 v[210:213], v126 offset:1600
	ds_read_b128 v[222:225], v126 offset:2368
	ds_read_b128 v[214:217], v126 offset:1856
	s_waitcnt lgkmcnt(5)
	v_pk_mul_f32 v[250:251], v[8:9], v[184:185]
	v_pk_fma_f32 v[250:251], v[10:11], v[186:187], v[250:251]
	v_add_f32_e32 v14, v250, v251
	v_pk_mul_f32 v[252:253], v[136:137], v[196:197] op_sel_hi:[0,1]
	v_pk_mul_f32 v[254:255], v[136:137], v[198:199] op_sel_hi:[0,1]
	v_add_f32_dpp v14, v14, v14 quad_perm:[1,0,3,2] row_mask:0xf bank_mask:0xf bound_ctrl:1
	v_pk_fma_f32 v[252:253], v[8:9], v[188:189], v[252:253]
	v_pk_fma_f32 v[254:255], v[10:11], v[190:191], v[254:255]
	v_add_f32_dpp v14, v14, v14 quad_perm:[2,3,0,1] row_mask:0xf bank_mask:0xf bound_ctrl:1
	ds_read_b128 v[228:231], v126 offset:2688
	ds_read_b128 v[240:243], v126 offset:3456
	v_add_f32_dpp v14, v14, v14 row_half_mirror row_mask:0xf bank_mask:0xf bound_ctrl:1
	ds_read_b128 v[232:235], v126 offset:2944
	ds_read_b128 v[244:247], v126 offset:3712
	v_add_f32_dpp v14, v14, v14 row_mirror row_mask:0xf bank_mask:0xf bound_ctrl:1
	v_pk_fma_f32 v[10:11], v[14:15], v[194:195], v[254:255] op_sel_hi:[0,1,1]
	v_pk_fma_f32 v[8:9], v[14:15], v[192:193], v[252:253] op_sel_hi:[0,1,1]
	ds_read_b128 v[236:239], v126 offset:3200
	s_waitcnt lgkmcnt(5)
	v_pk_mul_f32 v[250:251], v[8:9], v[206:207]
	v_pk_fma_f32 v[250:251], v[10:11], v[208:209], v[250:251]
	v_add_f32_e32 v14, v250, v251
	v_pk_mul_f32 v[252:253], v[136:137], v[218:219] op_sel:[1,0] op_sel_hi:[1,1]
	v_pk_mul_f32 v[254:255], v[136:137], v[220:221] op_sel:[1,0] op_sel_hi:[1,1]
	v_add_f32_dpp v14, v14, v14 quad_perm:[1,0,3,2] row_mask:0xf bank_mask:0xf bound_ctrl:1
	v_pk_fma_f32 v[252:253], v[8:9], v[210:211], v[252:253]
	v_pk_fma_f32 v[254:255], v[10:11], v[212:213], v[254:255]
	v_add_f32_dpp v14, v14, v14 quad_perm:[2,3,0,1] row_mask:0xf bank_mask:0xf bound_ctrl:1
	v_pk_mul_f32 v[12:13], v[8:9], v[200:201]
	v_pk_fma_f32 v[12:13], v[10:11], v[202:203], v[12:13]
	v_add_f32_dpp v14, v14, v14 row_half_mirror row_mask:0xf bank_mask:0xf bound_ctrl:1
	v_add_f32_e32 v18, v12, v13
	s_nop 0
	v_add_f32_dpp v14, v14, v14 row_mirror row_mask:0xf bank_mask:0xf bound_ctrl:1
	v_pk_fma_f32 v[10:11], v[14:15], v[216:217], v[254:255] op_sel_hi:[0,1,1]
	v_pk_fma_f32 v[8:9], v[14:15], v[214:215], v[252:253] op_sel_hi:[0,1,1]
	ds_read_b128 v[184:187], v126 offset:4032
	ds_read_b128 v[196:199], v126 offset:4800
	ds_read_b128 v[188:191], v126 offset:4288
	ds_read_b128 v[200:203], v126 offset:5056
	ds_read_b128 v[192:195], v126 offset:4544
	s_waitcnt lgkmcnt(5)
	v_pk_mul_f32 v[250:251], v[8:9], v[228:229]
	v_pk_fma_f32 v[250:251], v[10:11], v[230:231], v[250:251]
	v_add_f32_e32 v14, v250, v251
	v_pk_mul_f32 v[252:253], v[138:139], v[240:241] op_sel_hi:[0,1]
	v_pk_mul_f32 v[254:255], v[138:139], v[242:243] op_sel_hi:[0,1]
	v_add_f32_dpp v14, v14, v14 quad_perm:[1,0,3,2] row_mask:0xf bank_mask:0xf bound_ctrl:1
	v_pk_fma_f32 v[252:253], v[8:9], v[232:233], v[252:253]
	v_pk_fma_f32 v[254:255], v[10:11], v[234:235], v[254:255]
	v_add_f32_dpp v14, v14, v14 quad_perm:[2,3,0,1] row_mask:0xf bank_mask:0xf bound_ctrl:1
	v_pk_mul_f32 v[12:13], v[8:9], v[222:223]
	v_pk_fma_f32 v[12:13], v[10:11], v[224:225], v[12:13]
	v_add_f32_dpp v14, v14, v14 row_half_mirror row_mask:0xf bank_mask:0xf bound_ctrl:1
	v_add_f32_e32 v19, v12, v13
	s_nop 0
	v_add_f32_dpp v14, v14, v14 row_mirror row_mask:0xf bank_mask:0xf bound_ctrl:1
	v_pk_fma_f32 v[10:11], v[14:15], v[238:239], v[254:255] op_sel_hi:[0,1,1]
	v_pk_fma_f32 v[8:9], v[14:15], v[236:237], v[252:253] op_sel_hi:[0,1,1]
	ds_read_b128 v[140:143], v127 offset:16
	ds_read_b128 v[206:209], v126 offset:5376
	ds_read_b128 v[218:221], v126 offset:6144
	ds_read_b128 v[210:213], v126 offset:5632
	ds_read_b128 v[222:225], v126 offset:6400
	ds_read_b128 v[214:217], v126 offset:5888
	s_waitcnt lgkmcnt(6)
	v_pk_mul_f32 v[250:251], v[8:9], v[184:185]
	v_pk_fma_f32 v[250:251], v[10:11], v[186:187], v[250:251]
	v_add_f32_e32 v14, v250, v251
	v_pk_mul_f32 v[252:253], v[138:139], v[196:197] op_sel:[1,0] op_sel_hi:[1,1]
	v_pk_mul_f32 v[254:255], v[138:139], v[198:199] op_sel:[1,0] op_sel_hi:[1,1]
	v_add_f32_dpp v14, v14, v14 quad_perm:[1,0,3,2] row_mask:0xf bank_mask:0xf bound_ctrl:1
	v_pk_fma_f32 v[252:253], v[8:9], v[188:189], v[252:253]
	v_pk_fma_f32 v[254:255], v[10:11], v[190:191], v[254:255]
	v_add_f32_dpp v14, v14, v14 quad_perm:[2,3,0,1] row_mask:0xf bank_mask:0xf bound_ctrl:1
	v_pk_mul_f32 v[12:13], v[8:9], v[244:245]
	v_pk_fma_f32 v[12:13], v[10:11], v[246:247], v[12:13]
	v_add_f32_dpp v14, v14, v14 row_half_mirror row_mask:0xf bank_mask:0xf bound_ctrl:1
	v_add_f32_e32 v20, v12, v13
	s_nop 0
	v_add_f32_dpp v14, v14, v14 row_mirror row_mask:0xf bank_mask:0xf bound_ctrl:1
	v_pk_fma_f32 v[10:11], v[14:15], v[194:195], v[254:255] op_sel_hi:[0,1,1]
	v_pk_fma_f32 v[8:9], v[14:15], v[192:193], v[252:253] op_sel_hi:[0,1,1]
	ds_read_b128 v[228:231], v126 offset:6720
	ds_read_b128 v[240:243], v126 offset:7488
	ds_read_b128 v[232:235], v126 offset:6976
	ds_read_b128 v[244:247], v126 offset:7744
	ds_read_b128 v[236:239], v126 offset:7232
	s_waitcnt lgkmcnt(5)
	v_pk_mul_f32 v[250:251], v[8:9], v[206:207]
	v_pk_fma_f32 v[250:251], v[10:11], v[208:209], v[250:251]
	v_add_f32_e32 v14, v250, v251
	v_pk_mul_f32 v[252:253], v[140:141], v[218:219] op_sel_hi:[0,1]
	v_pk_mul_f32 v[254:255], v[140:141], v[220:221] op_sel_hi:[0,1]
	v_add_f32_dpp v14, v14, v14 quad_perm:[1,0,3,2] row_mask:0xf bank_mask:0xf bound_ctrl:1
	v_pk_fma_f32 v[252:253], v[8:9], v[210:211], v[252:253]
	v_pk_fma_f32 v[254:255], v[10:11], v[212:213], v[254:255]
	v_add_f32_dpp v14, v14, v14 quad_perm:[2,3,0,1] row_mask:0xf bank_mask:0xf bound_ctrl:1
	v_pk_mul_f32 v[12:13], v[8:9], v[200:201]
	v_pk_fma_f32 v[12:13], v[10:11], v[202:203], v[12:13]
	v_add_f32_dpp v14, v14, v14 row_half_mirror row_mask:0xf bank_mask:0xf bound_ctrl:1
	v_add_f32_e32 v21, v12, v13
	s_nop 0
	v_add_f32_dpp v14, v14, v14 row_mirror row_mask:0xf bank_mask:0xf bound_ctrl:1
	v_pk_fma_f32 v[10:11], v[14:15], v[216:217], v[254:255] op_sel_hi:[0,1,1]
	v_pk_fma_f32 v[8:9], v[14:15], v[214:215], v[252:253] op_sel_hi:[0,1,1]
	ds_read_b128 v[184:187], v126 offset:8064
	ds_read_b128 v[196:199], v126 offset:8832
	ds_read_b128 v[188:191], v126 offset:8320
	ds_read_b128 v[200:203], v126 offset:9088
	ds_read_b128 v[192:195], v126 offset:8576
	s_waitcnt lgkmcnt(5)
	v_pk_mul_f32 v[250:251], v[8:9], v[228:229]
	v_pk_fma_f32 v[250:251], v[10:11], v[230:231], v[250:251]
	v_add_f32_e32 v14, v250, v251
	v_pk_mul_f32 v[252:253], v[140:141], v[240:241] op_sel:[1,0] op_sel_hi:[1,1]
	v_pk_mul_f32 v[254:255], v[140:141], v[242:243] op_sel:[1,0] op_sel_hi:[1,1]
	v_add_f32_dpp v14, v14, v14 quad_perm:[1,0,3,2] row_mask:0xf bank_mask:0xf bound_ctrl:1
	v_pk_fma_f32 v[252:253], v[8:9], v[232:233], v[252:253]
	v_pk_fma_f32 v[254:255], v[10:11], v[234:235], v[254:255]
	v_add_f32_dpp v14, v14, v14 quad_perm:[2,3,0,1] row_mask:0xf bank_mask:0xf bound_ctrl:1
	v_pk_mul_f32 v[12:13], v[8:9], v[222:223]
	v_pk_fma_f32 v[12:13], v[10:11], v[224:225], v[12:13]
	v_add_f32_dpp v14, v14, v14 row_half_mirror row_mask:0xf bank_mask:0xf bound_ctrl:1
	v_add_f32_e32 v22, v12, v13
	s_nop 0
	v_add_f32_dpp v14, v14, v14 row_mirror row_mask:0xf bank_mask:0xf bound_ctrl:1
	v_pk_fma_f32 v[10:11], v[14:15], v[238:239], v[254:255] op_sel_hi:[0,1,1]
	v_pk_fma_f32 v[8:9], v[14:15], v[236:237], v[252:253] op_sel_hi:[0,1,1]
	ds_read_b128 v[206:209], v126 offset:9408
	ds_read_b128 v[218:221], v126 offset:10176
	ds_read_b128 v[210:213], v126 offset:9664
	ds_read_b128 v[222:225], v126 offset:10432
	ds_read_b128 v[214:217], v126 offset:9920
	s_waitcnt lgkmcnt(5)
	v_pk_mul_f32 v[250:251], v[8:9], v[184:185]
	v_pk_fma_f32 v[250:251], v[10:11], v[186:187], v[250:251]
	v_add_f32_e32 v14, v250, v251
	v_pk_mul_f32 v[252:253], v[142:143], v[196:197] op_sel_hi:[0,1]
	v_pk_mul_f32 v[254:255], v[142:143], v[198:199] op_sel_hi:[0,1]
	v_add_f32_dpp v14, v14, v14 quad_perm:[1,0,3,2] row_mask:0xf bank_mask:0xf bound_ctrl:1
	v_pk_fma_f32 v[252:253], v[8:9], v[188:189], v[252:253]
	v_pk_fma_f32 v[254:255], v[10:11], v[190:191], v[254:255]
	v_add_f32_dpp v14, v14, v14 quad_perm:[2,3,0,1] row_mask:0xf bank_mask:0xf bound_ctrl:1
	v_pk_mul_f32 v[12:13], v[8:9], v[244:245]
	v_pk_fma_f32 v[12:13], v[10:11], v[246:247], v[12:13]
	v_add_f32_dpp v14, v14, v14 row_half_mirror row_mask:0xf bank_mask:0xf bound_ctrl:1
	v_add_f32_e32 v23, v12, v13
	s_nop 0
	v_add_f32_dpp v14, v14, v14 row_mirror row_mask:0xf bank_mask:0xf bound_ctrl:1
	v_pk_fma_f32 v[10:11], v[14:15], v[194:195], v[254:255] op_sel_hi:[0,1,1]
	v_pk_fma_f32 v[8:9], v[14:15], v[192:193], v[252:253] op_sel_hi:[0,1,1]
	ds_read_b128 v[136:139], v127 offset:32
	ds_read_b128 v[228:231], v126 offset:10752
	ds_read_b128 v[240:243], v126 offset:11520
	ds_read_b128 v[232:235], v126 offset:11008
	ds_read_b128 v[244:247], v126 offset:11776
	ds_read_b128 v[236:239], v126 offset:11264
	s_waitcnt lgkmcnt(6)
	v_pk_mul_f32 v[250:251], v[8:9], v[206:207]
	v_pk_fma_f32 v[250:251], v[10:11], v[208:209], v[250:251]
	v_add_f32_e32 v14, v250, v251
	v_pk_mul_f32 v[252:253], v[142:143], v[218:219] op_sel:[1,0] op_sel_hi:[1,1]
	v_pk_mul_f32 v[254:255], v[142:143], v[220:221] op_sel:[1,0] op_sel_hi:[1,1]
	v_add_f32_dpp v14, v14, v14 quad_perm:[1,0,3,2] row_mask:0xf bank_mask:0xf bound_ctrl:1
	v_pk_fma_f32 v[252:253], v[8:9], v[210:211], v[252:253]
	v_pk_fma_f32 v[254:255], v[10:11], v[212:213], v[254:255]
	v_add_f32_dpp v14, v14, v14 quad_perm:[2,3,0,1] row_mask:0xf bank_mask:0xf bound_ctrl:1
	v_pk_mul_f32 v[12:13], v[8:9], v[200:201]
	v_pk_fma_f32 v[12:13], v[10:11], v[202:203], v[12:13]
	v_add_f32_dpp v14, v14, v14 row_half_mirror row_mask:0xf bank_mask:0xf bound_ctrl:1
	v_add_f32_e32 v24, v12, v13
	s_nop 0
	v_add_f32_dpp v14, v14, v14 row_mirror row_mask:0xf bank_mask:0xf bound_ctrl:1
	v_pk_fma_f32 v[10:11], v[14:15], v[216:217], v[254:255] op_sel_hi:[0,1,1]
	v_pk_fma_f32 v[8:9], v[14:15], v[214:215], v[252:253] op_sel_hi:[0,1,1]
	ds_read_b128 v[184:187], v126 offset:12096
	ds_read_b128 v[196:199], v126 offset:12864
	ds_read_b128 v[188:191], v126 offset:12352
	ds_read_b128 v[200:203], v126 offset:13120
	ds_read_b128 v[192:195], v126 offset:12608
	s_waitcnt lgkmcnt(5)
	v_pk_mul_f32 v[250:251], v[8:9], v[228:229]
	v_pk_fma_f32 v[250:251], v[10:11], v[230:231], v[250:251]
	v_add_f32_e32 v14, v250, v251
	v_pk_mul_f32 v[252:253], v[136:137], v[240:241] op_sel_hi:[0,1]
	v_pk_mul_f32 v[254:255], v[136:137], v[242:243] op_sel_hi:[0,1]
	v_add_f32_dpp v14, v14, v14 quad_perm:[1,0,3,2] row_mask:0xf bank_mask:0xf bound_ctrl:1
	v_pk_fma_f32 v[252:253], v[8:9], v[232:233], v[252:253]
	v_pk_fma_f32 v[254:255], v[10:11], v[234:235], v[254:255]
	v_add_f32_dpp v14, v14, v14 quad_perm:[2,3,0,1] row_mask:0xf bank_mask:0xf bound_ctrl:1
	v_pk_mul_f32 v[12:13], v[8:9], v[222:223]
	v_pk_fma_f32 v[12:13], v[10:11], v[224:225], v[12:13]
	v_add_f32_dpp v14, v14, v14 row_half_mirror row_mask:0xf bank_mask:0xf bound_ctrl:1
	v_add_f32_e32 v25, v12, v13
	s_nop 0
	v_add_f32_dpp v14, v14, v14 row_mirror row_mask:0xf bank_mask:0xf bound_ctrl:1
	v_pk_fma_f32 v[10:11], v[14:15], v[238:239], v[254:255] op_sel_hi:[0,1,1]
	v_pk_fma_f32 v[8:9], v[14:15], v[236:237], v[252:253] op_sel_hi:[0,1,1]
	ds_read_b128 v[206:209], v126 offset:13440
	ds_read_b128 v[218:221], v126 offset:14208
	ds_read_b128 v[210:213], v126 offset:13696
	ds_read_b128 v[222:225], v126 offset:14464
	ds_read_b128 v[214:217], v126 offset:13952
	s_waitcnt vmcnt(0)
	s_xor_b32 s0, s11, 1
	v_lshl_add_u32 v170, s0, 10, v130
	s_mulk_i32 s0, 0x5400
	v_add_u32_e32 v82, s0, v79
	v_lshlrev_b32_e32 v34, 16, v74
	v_and_b32_e32 v35, 0xffff0000, v74
	v_lshlrev_b32_e32 v36, 16, v75
	v_and_b32_e32 v37, 0xffff0000, v75
	v_lshl_add_u32 v83, v50, 2, v82
	v_pk_mul_f32 v[38:39], v[0:1], v[34:35]
	v_pk_mul_f32 v[40:41], v[2:3], v[36:37]
	v_lshlrev_b32_e32 v120, 16, v72
	v_pk_mul_f32 v[42:43], v[78:79], v[38:39] op_sel_hi:[0,1] neg_lo:[1,0] neg_hi:[1,0]
	v_pk_mul_f32 v[44:45], v[78:79], v[40:41] op_sel_hi:[0,1] neg_lo:[1,0] neg_hi:[1,0]
	v_and_b32_e32 v121, 0xffff0000, v72
	v_lshlrev_b32_e32 v122, 16, v73
	v_and_b32_e32 v123, 0xffff0000, v73
	ds_write_b128 v83, v[42:45]
	v_lshlrev_b32_e32 v38, 16, v76
	v_and_b32_e32 v39, 0xffff0000, v76
	v_lshlrev_b32_e32 v40, 16, v77
	v_and_b32_e32 v41, 0xffff0000, v77
	v_pk_add_f32 v[38:39], v[38:39], 1.0 op_sel_hi:[1,0] neg_lo:[1,0] neg_hi:[1,0]
	v_pk_add_f32 v[40:41], v[40:41], 1.0 op_sel_hi:[1,0] neg_lo:[1,0] neg_hi:[1,0]
	v_lshl_add_u32 v85, v48, 2, v82
	ds_write_b128 v83, v[38:41] offset:256
	v_pk_mul_f32 v[38:39], v[42:43], v[120:121] neg_lo:[1,0] neg_hi:[1,0]
	v_pk_mul_f32 v[40:41], v[44:45], v[122:123] neg_lo:[1,0] neg_hi:[1,0]
	v_pk_add_f32 v[120:121], v[120:121], -1.0 op_sel_hi:[1,0]
	v_pk_add_f32 v[122:123], v[122:123], -1.0 op_sel_hi:[1,0]
	ds_write_b128 v83, v[38:41] offset:512
	v_pk_fma_f32 v[120:121], v[4:5], v[120:121], 1.0 op_sel_hi:[1,1,0]
	v_pk_fma_f32 v[122:123], v[6:7], v[122:123], 1.0 op_sel_hi:[1,1,0]
	v_lshlrev_b32_e32 v42, 16, v62
	v_and_b32_e32 v43, 0xffff0000, v62
	v_pk_mul_f32 v[120:121], v[120:121], v[34:35]
	v_pk_mul_f32 v[122:123], v[122:123], v[36:37]
	v_lshlrev_b32_e32 v44, 16, v63
	v_and_b32_e32 v45, 0xffff0000, v63
	v_lshlrev_b32_e32 v84, 16, v102
	ds_write_b128 v83, v[120:123] offset:768
	ds_write_b128 v83, v[42:45] offset:1024
	ds_write_b32 v85, v84 offset:1280
	ds_write_b32 v170, v84
	s_cmpk_eq_i32 s6, 0x20e0
	s_cbranch_scc1 .Lscan_pf_skip
	s_cmp_eq_u32 s10, 14
	s_cselect_b64 vcc, -1, 0
	v_add_u32_e32 v131, v132, v131
	v_cndmask_b32_e32 v131, v131, v133, vcc
	v_lshl_add_u32 v34, v131, 11, v58
	v_lshl_add_u32 v35, v131, 6, v134
	v_lshl_add_u32 v36, v131, 11, v60
	global_load_dwordx2 v[74:75], v34, s[2:3]
	global_load_dwordx2 v[62:63], v34, s[90:91]
	global_load_dwordx2 v[76:77], v34, s[24:25]
	global_load_dword v78, v35, s[74:75]
	global_load_dwordx2 v[72:73], v34, s[20:21]
	global_load_ushort v102, v36, s[100:101]
.Lscan_pf_skip:
	s_waitcnt lgkmcnt(12)
	v_pk_mul_f32 v[250:251], v[8:9], v[184:185]
	v_pk_fma_f32 v[250:251], v[10:11], v[186:187], v[250:251]
	v_add_f32_e32 v14, v250, v251
	v_pk_mul_f32 v[252:253], v[136:137], v[196:197] op_sel:[1,0] op_sel_hi:[1,1]
	v_pk_mul_f32 v[254:255], v[136:137], v[198:199] op_sel:[1,0] op_sel_hi:[1,1]
	v_add_f32_dpp v14, v14, v14 quad_perm:[1,0,3,2] row_mask:0xf bank_mask:0xf bound_ctrl:1
	v_pk_fma_f32 v[252:253], v[8:9], v[188:189], v[252:253]
	v_pk_fma_f32 v[254:255], v[10:11], v[190:191], v[254:255]
	v_add_f32_dpp v14, v14, v14 quad_perm:[2,3,0,1] row_mask:0xf bank_mask:0xf bound_ctrl:1
	v_pk_mul_f32 v[12:13], v[8:9], v[244:245]
	v_pk_fma_f32 v[12:13], v[10:11], v[246:247], v[12:13]
	v_add_f32_dpp v14, v14, v14 row_half_mirror row_mask:0xf bank_mask:0xf bound_ctrl:1
	v_add_f32_e32 v26, v12, v13
	s_nop 0
	v_add_f32_dpp v14, v14, v14 row_mirror row_mask:0xf bank_mask:0xf bound_ctrl:1
	v_pk_fma_f32 v[10:11], v[14:15], v[194:195], v[254:255] op_sel_hi:[0,1,1]
	v_pk_fma_f32 v[8:9], v[14:15], v[192:193], v[252:253] op_sel_hi:[0,1,1]
	ds_read_b128 v[228:231], v126 offset:14784
	ds_read_b128 v[240:243], v126 offset:15552
	ds_read_b128 v[232:235], v126 offset:15040
	ds_read_b128 v[244:247], v126 offset:15808
	ds_read_b128 v[236:239], v126 offset:15296
	s_waitcnt lgkmcnt(12)
	v_pk_mul_f32 v[250:251], v[8:9], v[206:207]
	v_pk_fma_f32 v[250:251], v[10:11], v[208:209], v[250:251]
	v_add_f32_e32 v14, v250, v251
	v_pk_mul_f32 v[252:253], v[138:139], v[218:219] op_sel_hi:[0,1]
	v_pk_mul_f32 v[254:255], v[138:139], v[220:221] op_sel_hi:[0,1]
	v_add_f32_dpp v14, v14, v14 quad_perm:[1,0,3,2] row_mask:0xf bank_mask:0xf bound_ctrl:1
	v_pk_fma_f32 v[252:253], v[8:9], v[210:211], v[252:253]
	v_pk_fma_f32 v[254:255], v[10:11], v[212:213], v[254:255]
	v_add_f32_dpp v14, v14, v14 quad_perm:[2,3,0,1] row_mask:0xf bank_mask:0xf bound_ctrl:1
	v_pk_mul_f32 v[12:13], v[8:9], v[200:201]
	v_pk_fma_f32 v[12:13], v[10:11], v[202:203], v[12:13]
	v_add_f32_dpp v14, v14, v14 row_half_mirror row_mask:0xf bank_mask:0xf bound_ctrl:1
	v_add_f32_e32 v27, v12, v13
	s_nop 0
	v_add_f32_dpp v14, v14, v14 row_mirror row_mask:0xf bank_mask:0xf bound_ctrl:1
	v_pk_fma_f32 v[10:11], v[14:15], v[216:217], v[254:255] op_sel_hi:[0,1,1]
	v_pk_fma_f32 v[8:9], v[14:15], v[214:215], v[252:253] op_sel_hi:[0,1,1]
	ds_read_b128 v[140:143], v127 offset:48
	ds_read_b128 v[184:187], v126 offset:16128
	ds_read_b128 v[196:199], v126 offset:16896
	ds_read_b128 v[188:191], v126 offset:16384
	ds_read_b128 v[200:203], v126 offset:17152
	ds_read_b128 v[192:195], v126 offset:16640
	s_waitcnt lgkmcnt(6)
	v_pk_mul_f32 v[250:251], v[8:9], v[228:229]
	v_pk_fma_f32 v[250:251], v[10:11], v[230:231], v[250:251]
	v_add_f32_e32 v14, v250, v251
	v_pk_mul_f32 v[252:253], v[138:139], v[240:241] op_sel:[1,0] op_sel_hi:[1,1]
	v_pk_mul_f32 v[254:255], v[138:139], v[242:243] op_sel:[1,0] op_sel_hi:[1,1]
	v_add_f32_dpp v14, v14, v14 quad_perm:[1,0,3,2] row_mask:0xf bank_mask:0xf bound_ctrl:1
	v_pk_fma_f32 v[252:253], v[8:9], v[232:233], v[252:253]
	v_pk_fma_f32 v[254:255], v[10:11], v[234:235], v[254:255]
	v_add_f32_dpp v14, v14, v14 quad_perm:[2,3,0,1] row_mask:0xf bank_mask:0xf bound_ctrl:1
	v_pk_mul_f32 v[12:13], v[8:9], v[222:223]
	v_pk_fma_f32 v[12:13], v[10:11], v[224:225], v[12:13]
	v_add_f32_dpp v14, v14, v14 row_half_mirror row_mask:0xf bank_mask:0xf bound_ctrl:1
	v_add_f32_e32 v28, v12, v13
	s_nop 0
	v_add_f32_dpp v14, v14, v14 row_mirror row_mask:0xf bank_mask:0xf bound_ctrl:1
	v_pk_fma_f32 v[10:11], v[14:15], v[238:239], v[254:255] op_sel_hi:[0,1,1]
	v_pk_fma_f32 v[8:9], v[14:15], v[236:237], v[252:253] op_sel_hi:[0,1,1]
	ds_read_b128 v[206:209], v126 offset:17472
	ds_read_b128 v[218:221], v126 offset:18240
	ds_read_b128 v[210:213], v126 offset:17728
	ds_read_b128 v[222:225], v126 offset:18496
	ds_read_b128 v[214:217], v126 offset:17984
	s_waitcnt lgkmcnt(5)
	v_pk_mul_f32 v[250:251], v[8:9], v[184:185]
	v_pk_fma_f32 v[250:251], v[10:11], v[186:187], v[250:251]
	v_add_f32_e32 v14, v250, v251
	v_pk_mul_f32 v[252:253], v[140:141], v[196:197] op_sel_hi:[0,1]
	v_pk_mul_f32 v[254:255], v[140:141], v[198:199] op_sel_hi:[0,1]
	v_add_f32_dpp v14, v14, v14 quad_perm:[1,0,3,2] row_mask:0xf bank_mask:0xf bound_ctrl:1
	v_pk_fma_f32 v[252:253], v[8:9], v[188:189], v[252:253]
	v_pk_fma_f32 v[254:255], v[10:11], v[190:191], v[254:255]
	v_add_f32_dpp v14, v14, v14 quad_perm:[2,3,0,1] row_mask:0xf bank_mask:0xf bound_ctrl:1
	v_pk_mul_f32 v[12:13], v[8:9], v[244:245]
	v_pk_fma_f32 v[12:13], v[10:11], v[246:247], v[12:13]
	v_add_f32_dpp v14, v14, v14 row_half_mirror row_mask:0xf bank_mask:0xf bound_ctrl:1
	v_add_f32_e32 v29, v12, v13
	s_nop 0
	v_add_f32_dpp v14, v14, v14 row_mirror row_mask:0xf bank_mask:0xf bound_ctrl:1
	v_pk_fma_f32 v[10:11], v[14:15], v[194:195], v[254:255] op_sel_hi:[0,1,1]
	v_pk_fma_f32 v[8:9], v[14:15], v[192:193], v[252:253] op_sel_hi:[0,1,1]
	ds_read_b128 v[228:231], v126 offset:18816
	ds_read_b128 v[240:243], v126 offset:19584
	ds_read_b128 v[232:235], v126 offset:19072
	ds_read_b128 v[244:247], v126 offset:19840
	ds_read_b128 v[236:239], v126 offset:19328
	s_waitcnt lgkmcnt(5)
	v_pk_mul_f32 v[250:251], v[8:9], v[206:207]
	v_pk_fma_f32 v[250:251], v[10:11], v[208:209], v[250:251]
	v_add_f32_e32 v14, v250, v251
	v_pk_mul_f32 v[252:253], v[140:141], v[218:219] op_sel:[1,0] op_sel_hi:[1,1]
	v_pk_mul_f32 v[254:255], v[140:141], v[220:221] op_sel:[1,0] op_sel_hi:[1,1]
	v_add_f32_dpp v14, v14, v14 quad_perm:[1,0,3,2] row_mask:0xf bank_mask:0xf bound_ctrl:1
	v_pk_fma_f32 v[252:253], v[8:9], v[210:211], v[252:253]
	v_pk_fma_f32 v[254:255], v[10:11], v[212:213], v[254:255]
	v_add_f32_dpp v14, v14, v14 quad_perm:[2,3,0,1] row_mask:0xf bank_mask:0xf bound_ctrl:1
	v_pk_mul_f32 v[12:13], v[8:9], v[200:201]
	v_pk_fma_f32 v[12:13], v[10:11], v[202:203], v[12:13]
	v_add_f32_dpp v14, v14, v14 row_half_mirror row_mask:0xf bank_mask:0xf bound_ctrl:1
	v_add_f32_e32 v30, v12, v13
	s_nop 0
	v_add_f32_dpp v14, v14, v14 row_mirror row_mask:0xf bank_mask:0xf bound_ctrl:1
	v_pk_fma_f32 v[10:11], v[14:15], v[216:217], v[254:255] op_sel_hi:[0,1,1]
	v_pk_fma_f32 v[8:9], v[14:15], v[214:215], v[252:253] op_sel_hi:[0,1,1]
	ds_read_b128 v[184:187], v126 offset:20160
	ds_read_b128 v[196:199], v126 offset:20928
	ds_read_b128 v[188:191], v126 offset:20416
	ds_read_b128 v[200:203], v126 offset:21184
	ds_read_b128 v[192:195], v126 offset:20672
	s_waitcnt lgkmcnt(5)
	v_pk_mul_f32 v[250:251], v[8:9], v[228:229]
	v_pk_fma_f32 v[250:251], v[10:11], v[230:231], v[250:251]
	v_add_f32_e32 v14, v250, v251
	v_pk_mul_f32 v[252:253], v[142:143], v[240:241] op_sel_hi:[0,1]
	v_pk_mul_f32 v[254:255], v[142:143], v[242:243] op_sel_hi:[0,1]
	v_add_f32_dpp v14, v14, v14 quad_perm:[1,0,3,2] row_mask:0xf bank_mask:0xf bound_ctrl:1
	v_pk_fma_f32 v[252:253], v[8:9], v[232:233], v[252:253]
	v_pk_fma_f32 v[254:255], v[10:11], v[234:235], v[254:255]
	v_add_f32_dpp v14, v14, v14 quad_perm:[2,3,0,1] row_mask:0xf bank_mask:0xf bound_ctrl:1
	v_pk_mul_f32 v[12:13], v[8:9], v[222:223]
	v_pk_fma_f32 v[12:13], v[10:11], v[224:225], v[12:13]
	v_add_f32_dpp v14, v14, v14 row_half_mirror row_mask:0xf bank_mask:0xf bound_ctrl:1
	v_add_f32_e32 v31, v12, v13
	s_nop 0
	v_add_f32_dpp v14, v14, v14 row_mirror row_mask:0xf bank_mask:0xf bound_ctrl:1
	v_pk_fma_f32 v[10:11], v[14:15], v[238:239], v[254:255] op_sel_hi:[0,1,1]
	v_pk_fma_f32 v[8:9], v[14:15], v[236:237], v[252:253] op_sel_hi:[0,1,1]
	s_waitcnt lgkmcnt(0)
	v_pk_mul_f32 v[250:251], v[8:9], v[184:185]
	v_pk_fma_f32 v[250:251], v[10:11], v[186:187], v[250:251]
	v_add_f32_e32 v14, v250, v251
	v_pk_mul_f32 v[252:253], v[142:143], v[196:197] op_sel:[1,0] op_sel_hi:[1,1]
	v_pk_mul_f32 v[254:255], v[142:143], v[198:199] op_sel:[1,0] op_sel_hi:[1,1]
	v_add_f32_dpp v14, v14, v14 quad_perm:[1,0,3,2] row_mask:0xf bank_mask:0xf bound_ctrl:1
	v_pk_fma_f32 v[252:253], v[8:9], v[188:189], v[252:253]
	v_pk_fma_f32 v[254:255], v[10:11], v[190:191], v[254:255]
	v_add_f32_dpp v14, v14, v14 quad_perm:[2,3,0,1] row_mask:0xf bank_mask:0xf bound_ctrl:1
	v_pk_mul_f32 v[12:13], v[8:9], v[244:245]
	v_pk_fma_f32 v[12:13], v[10:11], v[246:247], v[12:13]
	v_add_f32_dpp v14, v14, v14 row_half_mirror row_mask:0xf bank_mask:0xf bound_ctrl:1
	v_add_f32_e32 v32, v12, v13
	s_nop 0
	v_add_f32_dpp v14, v14, v14 row_mirror row_mask:0xf bank_mask:0xf bound_ctrl:1
	v_pk_fma_f32 v[10:11], v[14:15], v[194:195], v[254:255] op_sel_hi:[0,1,1]
	v_pk_fma_f32 v[8:9], v[14:15], v[192:193], v[252:253] op_sel_hi:[0,1,1]
	v_pk_mul_f32 v[12:13], v[8:9], v[200:201]
	v_add_f32_dpp v34, v18, v18 row_mirror row_mask:0xf bank_mask:0x3 bound_ctrl:1
	v_pk_fma_f32 v[12:13], v[10:11], v[202:203], v[12:13]
	v_add_f32_dpp v35, v19, v19 row_mirror row_mask:0xf bank_mask:0x3 bound_ctrl:1
	v_add_f32_dpp v36, v20, v20 row_mirror row_mask:0xf bank_mask:0x3 bound_ctrl:1
	v_add_f32_e32 v33, v12, v13
	v_add_f32_dpp v37, v21, v21 row_mirror row_mask:0xf bank_mask:0x3 bound_ctrl:1
	v_add_f32_dpp v38, v22, v22 row_mirror row_mask:0xf bank_mask:0x3 bound_ctrl:1
	v_add_f32_dpp v39, v23, v23 row_mirror row_mask:0xf bank_mask:0x3 bound_ctrl:1
	v_add_f32_dpp v40, v24, v24 row_mirror row_mask:0xf bank_mask:0x3 bound_ctrl:1
	v_add_f32_dpp v41, v25, v25 row_mirror row_mask:0xf bank_mask:0x3 bound_ctrl:1
	v_add_f32_dpp v34, v26, v26 row_mirror row_mask:0xf bank_mask:0xc bound_ctrl:1
	v_add_f32_dpp v35, v27, v27 row_mirror row_mask:0xf bank_mask:0xc bound_ctrl:1
	v_add_f32_dpp v36, v28, v28 row_mirror row_mask:0xf bank_mask:0xc bound_ctrl:1
	v_add_f32_dpp v37, v29, v29 row_mirror row_mask:0xf bank_mask:0xc bound_ctrl:1
	v_add_f32_dpp v38, v30, v30 row_mirror row_mask:0xf bank_mask:0xc bound_ctrl:1
	v_add_f32_dpp v39, v31, v31 row_mirror row_mask:0xf bank_mask:0xc bound_ctrl:1
	v_add_f32_dpp v40, v32, v32 row_mirror row_mask:0xf bank_mask:0xc bound_ctrl:1
	v_add_f32_dpp v41, v33, v33 row_mirror row_mask:0xf bank_mask:0xc bound_ctrl:1
	v_add_f32_dpp v42, v34, v34 row_half_mirror row_mask:0xf bank_mask:0x5 bound_ctrl:1
	v_add_f32_dpp v43, v35, v35 row_half_mirror row_mask:0xf bank_mask:0x5 bound_ctrl:1
	v_add_f32_dpp v44, v36, v36 row_half_mirror row_mask:0xf bank_mask:0x5 bound_ctrl:1
	v_add_f32_dpp v45, v37, v37 row_half_mirror row_mask:0xf bank_mask:0x5 bound_ctrl:1
	v_add_f32_dpp v42, v38, v38 row_half_mirror row_mask:0xf bank_mask:0xa bound_ctrl:1
	v_add_f32_dpp v43, v39, v39 row_half_mirror row_mask:0xf bank_mask:0xa bound_ctrl:1
	v_add_f32_dpp v44, v40, v40 row_half_mirror row_mask:0xf bank_mask:0xa bound_ctrl:1
	v_add_f32_dpp v45, v41, v41 row_half_mirror row_mask:0xf bank_mask:0xa bound_ctrl:1
	v_cndmask_b32_e64 v80, v44, v42, s[42:43]
	v_cndmask_b32_e64 v121, v42, v44, s[42:43]
	v_cndmask_b32_e64 v82, v45, v43, s[42:43]
	v_cndmask_b32_e64 v122, v43, v45, s[42:43]
	s_nop 0
	s_nop 0
	v_add_f32_dpp v13, v121, v80 quad_perm:[2,3,0,1] row_mask:0xf bank_mask:0xf bound_ctrl:1
	v_add_f32_dpp v14, v122, v82 quad_perm:[2,3,0,1] row_mask:0xf bank_mask:0xf bound_ctrl:1
	v_cndmask_b32_e64 v12, v13, v14, s[44:45]
	v_cndmask_b32_e64 v13, v14, v13, s[44:45]
	v_lshl_add_u32 v16, v100, 11, v99
	v_add_u32_e32 v100, v132, v100
	v_add_f32_dpp v13, v12, v13 quad_perm:[1,0,3,2] row_mask:0xf bank_mask:0xf bound_ctrl:1
	s_cmp_eq_u32 s10, 15
	s_cselect_b64 vcc, -1, 0
	v_cvt_pk_bf16_f32 v14, v13, v13
	v_cndmask_b32_e32 v100, v100, v101, vcc
	global_store_short v16, v14, s[100:101]
	s_add_i32 s6, s6, 16
	s_add_i32 s10, s10, 1
	s_cmpk_eq_i32 s6, 0x20f0
	s_waitcnt lgkmcnt(0)
	s_barrier
	s_cbranch_scc0 .LBB0_774
	s_branch .LBB0_767
